# attn LSE/O hoist + scan pass2 unit balance + GEMM first-K-iter peel (no acc zeroing) + EpiRes loads upfront
# speedup vs baseline: 1.0066x; 1.0066x over previous
; #define GAS __attribute__((address_space(1)))
; template <int pass> __device__ __forceinline__ void scan_phase(LAS unsigned char* lds, const bf16* P  , bf16* OB, float* scr, const float* lb0, const float* lb1, int jl, const float* onorm, int u_lo, int u_hi) {
;     ...
;     for (int u = u_lo + blockIdx.x; u < u_hi; u += gridDim.x) {
;         const int sc = u & 7, h = (u >> 3) & 7, b = u >> 6;
;         const size_t tok0 = (size_t)b * SEQ + sc * 512;
;         f32x16 S[2];
; #pragma unroll
;         for (int i = 0; i < 16; ++i) { S[0][i] = 0.f; S[1][i] = 0.f; }
;         if (pass == 2) {
;             for (int p = 0; p < sc; ++p) { const GAS float* Tp = (const GAS float*)Tg + (size_t)(u - sc + p) * 16384 + wave * 2048 + (tid & 63); const GAS float* Dp = (const GAS float*)Dg + (size_t)(u - sc + p) * 4096 + kh * 2048 + (tid & 63);
;                 asm volatile("" : "+v"(Tp), "+v"(Dp));
; #pragma unroll
;                 for (int j2 = 0; j2 < 2; ++j2)
; #pragma unroll
;                     for (int i = 0; i < 16; ++i) S[j2][i] = Dp[(j2 * 16 + i) * 64] * S[j2][i] + Tp[(j2 * 16 + i) * 64]; }
;         }
.LBB0_67:
	s_add_i32 s36, s36, s66
	s_add_i32 s27, s27, s66
	s_xor_b32 s36, s36, 7
	s_xor_b32 s27, s27, 7
	s_cmpk_gt_i32 s36, 0x1ff
	s_cbranch_scc1 .LBB0_98

; #define PG8_STAGE(bufoff, gbase, voff) do { _Pragma("unroll") for (int _i = 0; _i < 2; ++_i) \
;         __builtin_amdgcn_global_load_lds((const unsigned*)((const char*)(gbase) + (voff)[_i]), (PG8_LAS unsigned*)(lds + (bufoff) + ldsw + _i * 8192), 16, 0, 0); } while (0)
; #define PG8_LDA(dst, b, h) do { _Pragma("unroll") for (int m = 0; m < 4; ++m) _Pragma("unroll") for (int k = 0; k < 2; ++k) dst[m][k] = *(const PG8_LAS bf16x8*)(lds + PG8_SA(b, h) + aoff + m * 2048 + k * 1024); } while (0)
; #define PG8_LDB(dst, b, h) do { _Pragma("unroll") for (int n = 0; n < 2; ++n) _Pragma("unroll") for (int k = 0; k < 2; ++k) dst[n][k] = *(const PG8_LAS bf16x8*)(lds + PG8_SB(b, h) + boff + n * 2048 + k * 1024); } while (0)
; #define PG8_MMA(ai, bj, At, Bt) do { __builtin_amdgcn_s_setprio(1); _Pragma("unroll") for (int m = 0; m < 4; ++m) _Pragma("unroll") for (int n = 0; n < 2; ++n) _Pragma("unroll") for (int k = 0; k < 2; ++k) \
;         acc[ai][bj][m][n] = __builtin_amdgcn_mfma_f32_16x16x32_bf16(Bt[n][k], At[m][k], acc[ai][bj][m][n], 0, 0, 0); __builtin_amdgcn_s_setprio(0); } while (0)
; #define PG8_WAIT_V(n) asm volatile("s_waitcnt vmcnt(" #n ")" ::: "memory")
; #define PG8_WAIT_L(n) asm volatile("s_waitcnt lgkmcnt(" #n ")" ::: "memory")
; #define PG8_BAR __builtin_amdgcn_s_barrier()
; #define PG8_SCHED __builtin_amdgcn_sched_barrier(0)
; template <class Epi, class Sched, bool ALIGN_EPI = false, bool SP2 = false>
; __device__ __forceinline__ void gemm_phase(PG8_LAS unsigned char* lds, const Gemm g, const Sched& S, const Epi& E) {
;     ...
;             if constexpr (SP2) {
;             PG8_LDB(B0, 0, 0); PG8_LDB(B1, 0, 1); PG8_SCHED; PG8_LDA(At, 0, 0); PG8_STAGE(PG8_SA(1, 1), a1 + hstep, voffA);
;             PG8_WAIT_V(8); PG8_WAIT_L(0); PG8_BAR; PG8_MMA(0, 0, At, B0); PG8_MMA(0, 1, At, B1); PG8_BAR; PG8_SCHED;
;             PG8_LDA(At, 0, 1); PG8_STAGE(PG8_SB(0, 0), b2, voffB); PG8_STAGE(PG8_SB(0, 1), b2 + hstep, voffB); PG8_STAGE(PG8_SA(0, 0), a2, voffA);
;             PG8_WAIT_V(8); PG8_WAIT_L(0); PG8_BAR; PG8_MMA(1, 0, At, B0); PG8_MMA(1, 1, At, B1); PG8_BAR; PG8_SCHED;
.LBB0_226:
	s_add_u32 s2, s12, 0x100
	s_addc_u32 s6, s13, 0
	s_add_u32 s4, s16, 0x80
	s_addc_u32 s5, s17, 0
	s_mov_b32 s7, 0
	s_add_i32 s9, s7, 2
	s_add_u32 s12, s4, 0x80
	s_addc_u32 s13, s5, 0
	s_add_i32 s77, 0, 0x10000
	s_cmp_eq_u32 s91, s7
	s_cselect_b32 s13, s43, s13
	s_cselect_b32 s12, s42, s12
	s_cselect_b32 s17, s63, s6
	s_cselect_b32 s16, s62, s2
	s_add_i32 s7, 0, 0x14000
	v_add_u32_e32 v142, s77, v200
	v_add_u32_e32 v172, s7, v200
	s_waitcnt lgkmcnt(0)
	ds_read_b128 v[130:133], v142
	ds_read_b128 v[134:137], v142 offset:1024
	ds_read_b128 v[138:141], v142 offset:2048
	ds_read_b128 v[142:145], v142 offset:3072
	ds_read_b128 v[146:149], v172
	ds_read_b128 v[150:153], v172 offset:1024
	ds_read_b128 v[154:157], v172 offset:2048
	ds_read_b128 v[172:175], v172 offset:3072
	v_lshl_add_u64 v[188:189], s[4:5], 0, v[170:171]
	s_add_i32 m0, s36, 0xc000
	ds_read_b128 v[176:179], v202
	ds_read_b128 v[180:183], v202 offset:1024
	ds_read_b128 v[184:187], v202 offset:2048
	ds_read_b128 v[204:207], v202 offset:3072
	ds_read_b128 v[208:211], v202 offset:4096
	ds_read_b128 v[212:215], v202 offset:5120
	ds_read_b128 v[216:219], v202 offset:6144
	ds_read_b128 v[220:223], v202 offset:7168
	global_load_lds_dwordx4 v[188:189], off
	v_lshl_add_u64 v[188:189], s[4:5], 0, v[168:169]
	s_add_i32 m0, s36, 0xe000
	s_nop 0
	global_load_lds_dwordx4 v[188:189], off
	s_waitcnt vmcnt(8)
	s_waitcnt lgkmcnt(0)
	s_barrier
	s_setprio 1
	s_waitcnt lgkmcnt(0)
	v_mfma_f32_16x16x32_bf16 v[126:129], v[130:133], v[176:179], 0
	v_mfma_f32_16x16x32_bf16 v[122:125], v[138:141], v[176:179], 0
	v_mfma_f32_16x16x32_bf16 v[110:113], v[130:133], v[184:187], 0
	v_mfma_f32_16x16x32_bf16 v[106:109], v[138:141], v[184:187], 0
	v_mfma_f32_16x16x32_bf16 v[94:97], v[130:133], v[208:211], 0
	v_mfma_f32_16x16x32_bf16 v[90:93], v[138:141], v[208:211], 0
	v_mfma_f32_16x16x32_bf16 v[78:81], v[130:133], v[216:219], 0
	v_mfma_f32_16x16x32_bf16 v[74:77], v[138:141], v[216:219], 0
	v_mfma_f32_16x16x32_bf16 v[126:129], v[134:137], v[180:183], v[126:129]
	v_mfma_f32_16x16x32_bf16 v[122:125], v[142:145], v[180:183], v[122:125]
	v_mfma_f32_16x16x32_bf16 v[110:113], v[134:137], v[204:207], v[110:113]
	v_mfma_f32_16x16x32_bf16 v[106:109], v[142:145], v[204:207], v[106:109]
	v_mfma_f32_16x16x32_bf16 v[94:97], v[134:137], v[212:215], v[94:97]
	v_mfma_f32_16x16x32_bf16 v[90:93], v[142:145], v[212:215], v[90:93]
	v_mfma_f32_16x16x32_bf16 v[78:81], v[134:137], v[220:223], v[78:81]
	v_mfma_f32_16x16x32_bf16 v[74:77], v[142:145], v[220:223], v[74:77]
	s_setprio 0
	s_setprio 1
	v_mfma_f32_16x16x32_bf16 v[118:121], v[146:149], v[176:179], 0
	v_mfma_f32_16x16x32_bf16 v[114:117], v[154:157], v[176:179], 0
	v_mfma_f32_16x16x32_bf16 v[102:105], v[146:149], v[184:187], 0
	v_mfma_f32_16x16x32_bf16 v[98:101], v[154:157], v[184:187], 0
	v_mfma_f32_16x16x32_bf16 v[86:89], v[146:149], v[208:211], 0
	v_mfma_f32_16x16x32_bf16 v[82:85], v[154:157], v[208:211], 0
	v_mfma_f32_16x16x32_bf16 v[70:73], v[146:149], v[216:219], 0
	v_mfma_f32_16x16x32_bf16 v[66:69], v[154:157], v[216:219], 0
	v_mfma_f32_16x16x32_bf16 v[118:121], v[150:153], v[180:183], v[118:121]
	v_mfma_f32_16x16x32_bf16 v[114:117], v[172:175], v[180:183], v[114:117]
	v_mfma_f32_16x16x32_bf16 v[102:105], v[150:153], v[204:207], v[102:105]
	v_mfma_f32_16x16x32_bf16 v[98:101], v[172:175], v[204:207], v[98:101]
	v_mfma_f32_16x16x32_bf16 v[86:89], v[150:153], v[212:215], v[86:89]
	v_mfma_f32_16x16x32_bf16 v[82:85], v[172:175], v[212:215], v[82:85]
	v_mfma_f32_16x16x32_bf16 v[70:73], v[150:153], v[220:223], v[70:73]
	v_mfma_f32_16x16x32_bf16 v[66:69], v[172:175], v[220:223], v[66:69]
	s_setprio 0
	s_barrier
	s_add_i32 s77, s77, s21
	v_lshl_add_u64 v[188:189], s[16:17], 0, v[0:1]
	s_mov_b32 m0, s77
	ds_read_b128 v[176:179], v202 offset:16384
	ds_read_b128 v[180:183], v202 offset:17408
	ds_read_b128 v[184:187], v202 offset:18432
	ds_read_b128 v[204:207], v202 offset:19456
	ds_read_b128 v[208:211], v202 offset:20480
	ds_read_b128 v[212:215], v202 offset:21504
	ds_read_b128 v[216:219], v202 offset:22528
	ds_read_b128 v[220:223], v202 offset:23552
	global_load_lds_dwordx4 v[188:189], off
	s_add_i32 m0, s77, 0x2000
	v_lshl_add_u64 v[224:225], s[16:17], 0, v[164:165]
	s_add_u32 s16, s16, s50
	s_addc_u32 s17, s17, 0
	s_add_i32 s7, s7, s21
	global_load_lds_dwordx4 v[224:225], off
	v_lshl_add_u64 v[226:227], s[16:17], 0, v[0:1]
	s_mov_b32 m0, s7
	v_lshl_add_u64 v[228:229], s[16:17], 0, v[164:165]
	global_load_lds_dwordx4 v[226:227], off
	s_add_i32 m0, s7, 0x2000
	v_lshl_add_u64 v[230:231], s[12:13], 0, v[158:159]
	global_load_lds_dwordx4 v[228:229], off
	s_mov_b32 m0, s36
	v_lshl_add_u64 v[232:233], s[12:13], 0, v[160:161]
	global_load_lds_dwordx4 v[230:231], off
	s_mov_b32 m0, s37
	s_nop 0
	global_load_lds_dwordx4 v[232:233], off
	s_waitcnt vmcnt(8)
	s_waitcnt lgkmcnt(0)
	s_barrier
; #define PG8_STAGE(bufoff, gbase, voff) do { _Pragma("unroll") for (int _i = 0; _i < 2; ++_i) \
;         __builtin_amdgcn_global_load_lds((const unsigned*)((const char*)(gbase) + (voff)[_i]), (PG8_LAS unsigned*)(lds + (bufoff) + ldsw + _i * 8192), 16, 0, 0); } while (0)
; #define PG8_LDA(dst, b, h) do { _Pragma("unroll") for (int m = 0; m < 4; ++m) _Pragma("unroll") for (int k = 0; k < 2; ++k) dst[m][k] = *(const PG8_LAS bf16x8*)(lds + PG8_SA(b, h) + aoff + m * 2048 + k * 1024); } while (0)
; #define PG8_LDB(dst, b, h) do { _Pragma("unroll") for (int n = 0; n < 2; ++n) _Pragma("unroll") for (int k = 0; k < 2; ++k) dst[n][k] = *(const PG8_LAS bf16x8*)(lds + PG8_SB(b, h) + boff + n * 2048 + k * 1024); } while (0)
; #define PG8_MMA(ai, bj, At, Bt) do { __builtin_amdgcn_s_setprio(1); _Pragma("unroll") for (int m = 0; m < 4; ++m) _Pragma("unroll") for (int n = 0; n < 2; ++n) _Pragma("unroll") for (int k = 0; k < 2; ++k) \
;         acc[ai][bj][m][n] = __builtin_amdgcn_mfma_f32_16x16x32_bf16(Bt[n][k], At[m][k], acc[ai][bj][m][n], 0, 0, 0); __builtin_amdgcn_s_setprio(0); } while (0)
; #define PG8_WAIT_V(n) asm volatile("s_waitcnt vmcnt(" #n ")" ::: "memory")
; #define PG8_WAIT_L(n) asm volatile("s_waitcnt lgkmcnt(" #n ")" ::: "memory")
; #define PG8_BAR __builtin_amdgcn_s_barrier()
; #define PG8_SCHED __builtin_amdgcn_sched_barrier(0)
; template <class Epi, class Sched, bool ALIGN_EPI = false, bool SP2 = false>
; __device__ __forceinline__ void gemm_phase(PG8_LAS unsigned char* lds, const Gemm g, const Sched& S, const Epi& E) {
;     ...
;             PG8_WAIT_V(8); PG8_WAIT_L(0); PG8_BAR; PG8_MMA(1, 0, At, B0); PG8_MMA(1, 1, At, B1); PG8_BAR; PG8_SCHED;
;             PG8_LDB(B0, 1, 0); PG8_LDB(B1, 1, 1); PG8_SCHED; PG8_LDA(At, 1, 0); PG8_STAGE(PG8_SA(0, 1), a2 + hstep, voffA);
;             PG8_WAIT_V(8); PG8_WAIT_L(0); PG8_BAR; PG8_MMA(0, 0, At, B0); PG8_MMA(0, 1, At, B1); PG8_BAR; PG8_SCHED;
;             PG8_LDA(At, 1, 1); PG8_STAGE(PG8_SB(1, 0), b3, voffB); PG8_STAGE(PG8_SB(1, 1), b3 + hstep, voffB); PG8_STAGE(PG8_SA(1, 0), a3, voffA);
	s_setprio 1
	s_waitcnt lgkmcnt(0)
	v_mfma_f32_16x16x32_bf16 v[62:65], v[130:133], v[176:179], 0
	v_mfma_f32_16x16x32_bf16 v[58:61], v[138:141], v[176:179], 0
	v_mfma_f32_16x16x32_bf16 v[46:49], v[130:133], v[184:187], 0
	v_mfma_f32_16x16x32_bf16 v[42:45], v[138:141], v[184:187], 0
	v_mfma_f32_16x16x32_bf16 v[30:33], v[130:133], v[208:211], 0
	v_mfma_f32_16x16x32_bf16 v[26:29], v[138:141], v[208:211], 0
	v_mfma_f32_16x16x32_bf16 v[14:17], v[130:133], v[216:219], 0
	v_mfma_f32_16x16x32_bf16 v[10:13], v[138:141], v[216:219], 0
	v_mfma_f32_16x16x32_bf16 v[62:65], v[134:137], v[180:183], v[62:65]
	v_mfma_f32_16x16x32_bf16 v[58:61], v[142:145], v[180:183], v[58:61]
	v_mfma_f32_16x16x32_bf16 v[46:49], v[134:137], v[204:207], v[46:49]
	v_mfma_f32_16x16x32_bf16 v[42:45], v[142:145], v[204:207], v[42:45]
	v_mfma_f32_16x16x32_bf16 v[30:33], v[134:137], v[212:215], v[30:33]
	v_mfma_f32_16x16x32_bf16 v[26:29], v[142:145], v[212:215], v[26:29]
	v_mfma_f32_16x16x32_bf16 v[14:17], v[134:137], v[220:223], v[14:17]
	v_mfma_f32_16x16x32_bf16 v[10:13], v[142:145], v[220:223], v[10:13]
	s_setprio 0
	s_setprio 1
	v_mfma_f32_16x16x32_bf16 v[54:57], v[146:149], v[176:179], 0
	v_mfma_f32_16x16x32_bf16 v[50:53], v[154:157], v[176:179], 0
	v_mfma_f32_16x16x32_bf16 v[38:41], v[146:149], v[184:187], 0
	v_mfma_f32_16x16x32_bf16 v[34:37], v[154:157], v[184:187], 0
	v_mfma_f32_16x16x32_bf16 v[22:25], v[146:149], v[208:211], 0
	v_mfma_f32_16x16x32_bf16 v[18:21], v[154:157], v[208:211], 0
	v_mfma_f32_16x16x32_bf16 v[6:9], v[146:149], v[216:219], 0
	v_mfma_f32_16x16x32_bf16 v[2:5], v[154:157], v[216:219], 0
	v_mfma_f32_16x16x32_bf16 v[54:57], v[150:153], v[180:183], v[54:57]
	v_mfma_f32_16x16x32_bf16 v[50:53], v[172:175], v[180:183], v[50:53]
	v_mfma_f32_16x16x32_bf16 v[38:41], v[150:153], v[204:207], v[38:41]
	v_mfma_f32_16x16x32_bf16 v[34:37], v[172:175], v[204:207], v[34:37]
	v_mfma_f32_16x16x32_bf16 v[22:25], v[150:153], v[212:215], v[22:25]
	v_mfma_f32_16x16x32_bf16 v[18:21], v[172:175], v[212:215], v[18:21]
	v_mfma_f32_16x16x32_bf16 v[6:9], v[150:153], v[220:223], v[6:9]
	v_mfma_f32_16x16x32_bf16 v[2:5], v[172:175], v[220:223], v[2:5]
	s_setprio 0
	s_barrier
	s_add_i32 s7, 0, 0x18000
	s_add_i32 s16, 0, 0x1c000
	v_add_u32_e32 v142, s7, v200
	v_add_u32_e32 v172, s16, v200
	ds_read_b128 v[130:133], v142
	ds_read_b128 v[134:137], v142 offset:1024
	ds_read_b128 v[138:141], v142 offset:2048
	ds_read_b128 v[142:145], v142 offset:3072
	ds_read_b128 v[146:149], v172
	ds_read_b128 v[150:153], v172 offset:1024
	ds_read_b128 v[154:157], v172 offset:2048
	ds_read_b128 v[172:175], v172 offset:3072
	s_add_u32 s12, s12, s50
	s_addc_u32 s13, s13, 0
	s_mov_b32 m0, s64
	v_lshl_add_u64 v[234:235], s[12:13], 0, v[158:159]
	ds_read_b128 v[176:179], v202 offset:32768
	ds_read_b128 v[180:183], v202 offset:33792
	ds_read_b128 v[184:187], v202 offset:34816
	ds_read_b128 v[204:207], v202 offset:35840
	ds_read_b128 v[208:211], v202 offset:36864
	ds_read_b128 v[212:215], v202 offset:37888
	ds_read_b128 v[216:219], v202 offset:38912
	ds_read_b128 v[220:223], v202 offset:39936
	global_load_lds_dwordx4 v[234:235], off
	v_lshl_add_u64 v[234:235], s[12:13], 0, v[160:161]
	s_mov_b32 m0, s65
	s_nop 0
	global_load_lds_dwordx4 v[234:235], off
	s_waitcnt vmcnt(8)
	s_waitcnt lgkmcnt(0)
	s_barrier
	s_setprio 1
	s_waitcnt lgkmcnt(0)
	v_mfma_f32_16x16x32_bf16 v[126:129], v[130:133], v[176:179], v[126:129]
	v_mfma_f32_16x16x32_bf16 v[122:125], v[138:141], v[176:179], v[122:125]
	v_mfma_f32_16x16x32_bf16 v[110:113], v[130:133], v[184:187], v[110:113]
	v_mfma_f32_16x16x32_bf16 v[106:109], v[138:141], v[184:187], v[106:109]
	v_mfma_f32_16x16x32_bf16 v[94:97], v[130:133], v[208:211], v[94:97]
	v_mfma_f32_16x16x32_bf16 v[90:93], v[138:141], v[208:211], v[90:93]
	v_mfma_f32_16x16x32_bf16 v[78:81], v[130:133], v[216:219], v[78:81]
	v_mfma_f32_16x16x32_bf16 v[74:77], v[138:141], v[216:219], v[74:77]
	v_mfma_f32_16x16x32_bf16 v[126:129], v[134:137], v[180:183], v[126:129]
	v_mfma_f32_16x16x32_bf16 v[122:125], v[142:145], v[180:183], v[122:125]
	v_mfma_f32_16x16x32_bf16 v[110:113], v[134:137], v[204:207], v[110:113]
	v_mfma_f32_16x16x32_bf16 v[106:109], v[142:145], v[204:207], v[106:109]
	v_mfma_f32_16x16x32_bf16 v[94:97], v[134:137], v[212:215], v[94:97]
	v_mfma_f32_16x16x32_bf16 v[90:93], v[142:145], v[212:215], v[90:93]
	v_mfma_f32_16x16x32_bf16 v[78:81], v[134:137], v[220:223], v[78:81]
	v_mfma_f32_16x16x32_bf16 v[74:77], v[142:145], v[220:223], v[74:77]
	s_setprio 0
	s_setprio 1
	v_mfma_f32_16x16x32_bf16 v[118:121], v[146:149], v[176:179], v[118:121]
	v_mfma_f32_16x16x32_bf16 v[114:117], v[154:157], v[176:179], v[114:117]
	v_mfma_f32_16x16x32_bf16 v[102:105], v[146:149], v[184:187], v[102:105]
	v_mfma_f32_16x16x32_bf16 v[98:101], v[154:157], v[184:187], v[98:101]
	v_mfma_f32_16x16x32_bf16 v[86:89], v[146:149], v[208:211], v[86:89]
	v_mfma_f32_16x16x32_bf16 v[82:85], v[154:157], v[208:211], v[82:85]
	v_mfma_f32_16x16x32_bf16 v[70:73], v[146:149], v[216:219], v[70:73]
	v_mfma_f32_16x16x32_bf16 v[66:69], v[154:157], v[216:219], v[66:69]
	v_mfma_f32_16x16x32_bf16 v[118:121], v[150:153], v[180:183], v[118:121]
	v_mfma_f32_16x16x32_bf16 v[114:117], v[172:175], v[180:183], v[114:117]
	v_mfma_f32_16x16x32_bf16 v[102:105], v[150:153], v[204:207], v[102:105]
	v_mfma_f32_16x16x32_bf16 v[98:101], v[172:175], v[204:207], v[98:101]
	v_mfma_f32_16x16x32_bf16 v[86:89], v[150:153], v[212:215], v[86:89]
	v_mfma_f32_16x16x32_bf16 v[82:85], v[172:175], v[212:215], v[82:85]
	v_mfma_f32_16x16x32_bf16 v[70:73], v[150:153], v[220:223], v[70:73]
	v_mfma_f32_16x16x32_bf16 v[66:69], v[172:175], v[220:223], v[66:69]
	s_setprio 0
	s_barrier
; #define PG8_STAGE(bufoff, gbase, voff) do { _Pragma("unroll") for (int _i = 0; _i < 2; ++_i) \
;         __builtin_amdgcn_global_load_lds((const unsigned*)((const char*)(gbase) + (voff)[_i]), (PG8_LAS unsigned*)(lds + (bufoff) + ldsw + _i * 8192), 16, 0, 0); } while (0)
; #define PG8_LDA(dst, b, h) do { _Pragma("unroll") for (int m = 0; m < 4; ++m) _Pragma("unroll") for (int k = 0; k < 2; ++k) dst[m][k] = *(const PG8_LAS bf16x8*)(lds + PG8_SA(b, h) + aoff + m * 2048 + k * 1024); } while (0)
; #define PG8_MMA(ai, bj, At, Bt) do { __builtin_amdgcn_s_setprio(1); _Pragma("unroll") for (int m = 0; m < 4; ++m) _Pragma("unroll") for (int n = 0; n < 2; ++n) _Pragma("unroll") for (int k = 0; k < 2; ++k) \
;         acc[ai][bj][m][n] = __builtin_amdgcn_mfma_f32_16x16x32_bf16(Bt[n][k], At[m][k], acc[ai][bj][m][n], 0, 0, 0); __builtin_amdgcn_s_setprio(0); } while (0)
; #define PG8_WAIT_V(n) asm volatile("s_waitcnt vmcnt(" #n ")" ::: "memory")
; #define PG8_WAIT_L(n) asm volatile("s_waitcnt lgkmcnt(" #n ")" ::: "memory")
; #define PG8_BAR __builtin_amdgcn_s_barrier()
; #define PG8_SCHED __builtin_amdgcn_sched_barrier(0)
; template <class Epi, class Sched, bool ALIGN_EPI = false, bool SP2 = false>
; __device__ __forceinline__ void gemm_phase(PG8_LAS unsigned char* lds, const Gemm g, const Sched& S, const Epi& E) {
;     ...
;         const bool has_next = S.next(ui + 1, nxt);
;         const char* nA = has_next ? (const char*)g.A + (size_t)nxt.pm * tstep : cA; const char* nB = has_next ? (const char*)g.Bt + (size_t)nxt.pn * tstep : cB;
;         for (int t = 0; t < nt; t += 2) {
;             const bool last = (t == nt - 2);
;             const char* a1 = cA + (size_t)(t + 1) * kstep;
;             const char* a2 = last ? nA : cA + (size_t)(t + 2) * kstep; const char* b2 = last ? nB : cB + (size_t)(t + 2) * kstep;
;             const char* a3 = a2 + kstep; const char* b3 = b2 + kstep;
;     ...
;             PG8_LDA(At, 1, 1); PG8_STAGE(PG8_SB(1, 0), b3, voffB); PG8_STAGE(PG8_SB(1, 1), b3 + hstep, voffB); PG8_STAGE(PG8_SA(1, 0), a3, voffA);
;             PG8_WAIT_V(8); PG8_WAIT_L(0); PG8_BAR; PG8_MMA(1, 0, At, B0); PG8_MMA(1, 1, At, B1); PG8_BAR; PG8_SCHED;
	s_add_i32 s7, s7, s21
	v_lshl_add_u64 v[188:189], v[188:189], 0, s[98:99]
	s_mov_b32 m0, s7
	ds_read_b128 v[176:179], v202 offset:49152
	ds_read_b128 v[180:183], v202 offset:50176
	ds_read_b128 v[184:187], v202 offset:51200
	ds_read_b128 v[204:207], v202 offset:52224
	ds_read_b128 v[208:211], v202 offset:53248
	ds_read_b128 v[212:215], v202 offset:54272
	ds_read_b128 v[216:219], v202 offset:55296
	ds_read_b128 v[220:223], v202 offset:56320
	global_load_lds_dwordx4 v[188:189], off
	v_lshl_add_u64 v[188:189], v[224:225], 0, s[98:99]
	s_add_i32 m0, s7, 0x2000
	s_add_i32 s7, s16, s21
	global_load_lds_dwordx4 v[188:189], off
	v_lshl_add_u64 v[188:189], v[226:227], 0, s[98:99]
	s_mov_b32 m0, s7
	s_nop 0
	global_load_lds_dwordx4 v[188:189], off
	v_lshl_add_u64 v[188:189], v[228:229], 0, s[98:99]
	s_add_i32 m0, s7, 0x2000
	s_nop 0
	global_load_lds_dwordx4 v[188:189], off
	v_lshl_add_u64 v[188:189], v[230:231], 0, s[98:99]
	s_mov_b32 m0, s86
	s_nop 0
	global_load_lds_dwordx4 v[188:189], off
	v_lshl_add_u64 v[188:189], v[232:233], 0, s[98:99]
	s_mov_b32 m0, s87
	s_nop 0
	global_load_lds_dwordx4 v[188:189], off
	s_waitcnt vmcnt(8)
	s_waitcnt lgkmcnt(0)
	s_barrier
	s_setprio 1
	s_waitcnt lgkmcnt(0)
	v_mfma_f32_16x16x32_bf16 v[62:65], v[130:133], v[176:179], v[62:65]
	v_mfma_f32_16x16x32_bf16 v[58:61], v[138:141], v[176:179], v[58:61]
	v_mfma_f32_16x16x32_bf16 v[46:49], v[130:133], v[184:187], v[46:49]
	v_mfma_f32_16x16x32_bf16 v[42:45], v[138:141], v[184:187], v[42:45]
	v_mfma_f32_16x16x32_bf16 v[30:33], v[130:133], v[208:211], v[30:33]
	v_mfma_f32_16x16x32_bf16 v[26:29], v[138:141], v[208:211], v[26:29]
	v_mfma_f32_16x16x32_bf16 v[14:17], v[130:133], v[216:219], v[14:17]
	v_mfma_f32_16x16x32_bf16 v[10:13], v[138:141], v[216:219], v[10:13]
	v_mfma_f32_16x16x32_bf16 v[62:65], v[134:137], v[180:183], v[62:65]
	v_mfma_f32_16x16x32_bf16 v[58:61], v[142:145], v[180:183], v[58:61]
	v_mfma_f32_16x16x32_bf16 v[46:49], v[134:137], v[204:207], v[46:49]
	v_mfma_f32_16x16x32_bf16 v[42:45], v[142:145], v[204:207], v[42:45]
	v_mfma_f32_16x16x32_bf16 v[30:33], v[134:137], v[212:215], v[30:33]
	v_mfma_f32_16x16x32_bf16 v[26:29], v[142:145], v[212:215], v[26:29]
	v_mfma_f32_16x16x32_bf16 v[14:17], v[134:137], v[220:223], v[14:17]
	v_mfma_f32_16x16x32_bf16 v[10:13], v[142:145], v[220:223], v[10:13]
	s_setprio 0
	s_setprio 1
	v_mfma_f32_16x16x32_bf16 v[54:57], v[146:149], v[176:179], v[54:57]
	v_mfma_f32_16x16x32_bf16 v[50:53], v[154:157], v[176:179], v[50:53]
	v_mfma_f32_16x16x32_bf16 v[38:41], v[146:149], v[184:187], v[38:41]
	v_mfma_f32_16x16x32_bf16 v[34:37], v[154:157], v[184:187], v[34:37]
	v_mfma_f32_16x16x32_bf16 v[22:25], v[146:149], v[208:211], v[22:25]
	v_mfma_f32_16x16x32_bf16 v[18:21], v[154:157], v[208:211], v[18:21]
	v_mfma_f32_16x16x32_bf16 v[6:9], v[146:149], v[216:219], v[6:9]
	v_mfma_f32_16x16x32_bf16 v[2:5], v[154:157], v[216:219], v[2:5]
	v_mfma_f32_16x16x32_bf16 v[54:57], v[150:153], v[180:183], v[54:57]
	v_mfma_f32_16x16x32_bf16 v[50:53], v[172:175], v[180:183], v[50:53]
	v_mfma_f32_16x16x32_bf16 v[38:41], v[150:153], v[204:207], v[38:41]
	v_mfma_f32_16x16x32_bf16 v[34:37], v[172:175], v[204:207], v[34:37]
	v_mfma_f32_16x16x32_bf16 v[22:25], v[150:153], v[212:215], v[22:25]
	v_mfma_f32_16x16x32_bf16 v[18:21], v[172:175], v[212:215], v[18:21]
	v_mfma_f32_16x16x32_bf16 v[6:9], v[150:153], v[220:223], v[6:9]
	v_mfma_f32_16x16x32_bf16 v[2:5], v[172:175], v[220:223], v[2:5]
	s_setprio 0
	s_barrier
	s_add_u32 s2, s2, 0x100
	s_addc_u32 s6, s6, 0
	s_add_u32 s4, s4, 0x100
	s_addc_u32 s5, s5, 0
	s_cmp_ge_u32 s9, s90
	s_mov_b32 s7, s9
	s_cbranch_scc0 .LBB0_227
	s_branch .Lmy_k_exit

; #define PG8_BAR __builtin_amdgcn_s_barrier()
;     __device__ __forceinline__ void operator()(const f32x4 (&acc)[2][2][4][2], const Unit& u, int wr, int wc, int fr, int fq) const {
;         if (mode == 0) { EpiScaleBf16<0> e{O, ldc, ssq_in, O1, O2, split}; e(acc, u, wr, wc, fr, fq); }
;         else if (mode == 1) { EpiScaleBf16<1> e{O, ldc, ssq_in, O, O, 0}; e(acc, u, wr, wc, fr, fq); }
;         else { EpiRes e{xb, ssq_out}; e(acc, u, wr, wc, fr, fq); }
; template <class Epi, class Sched, bool ALIGN_EPI = false, bool SP2 = false>
; __device__ __forceinline__ void gemm_phase(PG8_LAS unsigned char* lds, const Gemm g, const Sched& S, const Epi& E) {
;     ...
;         if constexpr (ALIGN_EPI) { if (wr == 0) PG8_BAR; }
;         if constexpr (!Epi::AFTER_DRAIN) { E(acc, cur, wr, wc, fr, fq); S.done(cur); }
;         if (!has_next) break;
.Lmy_k_exit:
	s_and_b64 vcc, exec, s[58:59]
	s_cbranch_vccnz .LBB0_232
	s_cmp_lt_i32 s15, 1
	s_mov_b64 s[4:5], -1
	s_cbranch_scc0 .LBB0_233

; #define PG8_GAS __attribute__((address_space(1)))
; __device__ __forceinline__ unsigned cvt_pk_bf16(float lo, float hi) { unsigned r; asm volatile("v_cvt_pk_bf16_f32 %0, %1, %2" : "=v"(r) : "v"(lo), "v"(hi)); return r; }
;     __device__ __forceinline__ void operator()(const f32x4 (&acc)[2][2][4][2], const Unit& u, int wr, int wc, int fr, int fq) const {
;     ...
;         for (int ai = 0; ai < 2; ++ai) {
;             u32x4 bw[4][2];
; #pragma unroll
;             for (int m = 0; m < 4; ++m)
; #pragma unroll
;                 for (int bj = 0; bj < 2; ++bj) bw[m][bj] = *(const PG8_GAS u32x4*)(xb + (size_t)(row0 + ai * HALF + m * 16) * 1024 + col0 + bj * HALF);
; #pragma unroll
;             for (int m = 0; m < 4; ++m) {
;                 const int row = row0 + ai * HALF + m * 16; const size_t off = (size_t)row * 1024 + col0; float s = 0.f;
; #pragma unroll
;                 for (int bj = 0; bj < 2; ++bj) {
;                     f32x4 v0 = acc[ai][bj][m][0], v1 = acc[ai][bj][m][1]; const u32x4 b = bw[m][bj];
;                     v0[0] += __builtin_bit_cast(float, b.x << 16); v0[1] += __builtin_bit_cast(float, b.x & 0xffff0000u); v0[2] += __builtin_bit_cast(float, b.y << 16); v0[3] += __builtin_bit_cast(float, b.y & 0xffff0000u);
;                     v1[0] += __builtin_bit_cast(float, b.z << 16); v1[1] += __builtin_bit_cast(float, b.z & 0xffff0000u); v1[2] += __builtin_bit_cast(float, b.w << 16); v1[3] += __builtin_bit_cast(float, b.w & 0xffff0000u);
;                     u32x4 w; w.x = cvt_pk_bf16(v0[0], v0[1]); w.y = cvt_pk_bf16(v0[2], v0[3]); w.z = cvt_pk_bf16(v1[0], v1[1]); w.w = cvt_pk_bf16(v1[2], v1[3]);
;                     *(PG8_GAS u32x4*)(xb + off + bj * HALF) = w;
;                     s += (v0[0] * v0[0] + v0[1] * v0[1]) + (v0[2] * v0[2] + v0[3] * v0[3]) + (v1[0] * v1[0] + v1[1] * v1[1]) + (v1[2] * v1[2] + v1[3] * v1[3]); }
;                 s += __shfl_xor(s, 16); s += __shfl_xor(s, 32);
;                 if (fq == 0) ((PG8_GAS float*)ssq)[(size_t)row * 16 + u.pn * 4 + wc] = s; } }
.LBB0_233:
	s_cmp_lg_u32 s15, 1
	v_lshl_or_b32 v172, s27, 8, v201
	s_cbranch_scc0 .LBB0_251
	v_lshl_add_u32 v176, s26, 8, v199
	v_ashrrev_i32_e32 v173, 31, v172
	v_ashrrev_i32_e32 v177, 31, v176
	v_lshl_add_u64 v[174:175], v[172:173], 1, s[0:1]
	v_lshlrev_b64 v[130:131], 11, v[176:177]
	v_lshl_add_u64 v[208:209], v[174:175], 0, v[130:131]
	global_load_dwordx4 v[186:189], v[208:209], off
	global_load_dwordx4 v[204:207], v[208:209], off offset:256
	v_or_b32_e32 v182, 16, v176
	v_ashrrev_i32_e32 v183, 31, v182
	v_or_b32_e32 v178, 32, v176
	v_lshlrev_b64 v[130:131], 11, v[182:183]
	v_ashrrev_i32_e32 v179, 31, v178
	v_or_b32_e32 v154, 48, v176
	v_lshl_add_u64 v[184:185], v[174:175], 0, v[130:131]
	v_lshlrev_b64 v[130:131], 11, v[178:179]
	v_ashrrev_i32_e32 v155, 31, v154
	v_lshl_add_u64 v[180:181], v[174:175], 0, v[130:131]
	v_lshlrev_b64 v[130:131], 11, v[154:155]
	v_lshl_add_u64 v[156:157], v[174:175], 0, v[130:131]
	global_load_dwordx4 v[150:153], v[184:185], off
	global_load_dwordx4 v[146:149], v[184:185], off offset:256
	global_load_dwordx4 v[142:145], v[180:181], off
	global_load_dwordx4 v[138:141], v[180:181], off offset:256
	global_load_dwordx4 v[134:137], v[156:157], off
	global_load_dwordx4 v[130:133], v[156:157], off offset:256
	v_add_u32_e32 v254, 0x80, v176
	v_ashrrev_i32_e32 v255, 31, v254
	v_lshlrev_b64 v[252:253], 11, v[254:255]
	v_lshl_add_u64 v[252:253], v[174:175], 0, v[252:253]
	global_load_dwordx4 v[216:219], v[252:253], off
	global_load_dwordx4 v[220:223], v[252:253], off offset:256
	v_add_u32_e32 v254, 0x90, v176
	v_ashrrev_i32_e32 v255, 31, v254
	v_lshlrev_b64 v[252:253], 11, v[254:255]
	v_lshl_add_u64 v[252:253], v[174:175], 0, v[252:253]
	global_load_dwordx4 v[224:227], v[252:253], off
	global_load_dwordx4 v[228:231], v[252:253], off offset:256
	v_add_u32_e32 v254, 0xa0, v176
	v_ashrrev_i32_e32 v255, 31, v254
	v_lshlrev_b64 v[252:253], 11, v[254:255]
	v_lshl_add_u64 v[252:253], v[174:175], 0, v[252:253]
	global_load_dwordx4 v[232:235], v[252:253], off
	global_load_dwordx4 v[236:239], v[252:253], off offset:256
	v_add_u32_e32 v254, 0xb0, v176
	v_ashrrev_i32_e32 v255, 31, v254
	v_lshlrev_b64 v[252:253], 11, v[254:255]
	v_lshl_add_u64 v[252:253], v[174:175], 0, v[252:253]
	global_load_dwordx4 v[240:243], v[252:253], off
	global_load_dwordx4 v[244:247], v[252:253], off offset:256
	s_waitcnt vmcnt(8)
	v_lshlrev_b32_e32 v173, 16, v186
	v_and_b32_e32 v186, 0xffff0000, v186
	v_add_f32_e32 v203, v127, v186
	v_lshlrev_b32_e32 v186, 16, v187
	v_add_f32_e32 v210, v128, v186
	v_and_b32_e32 v186, 0xffff0000, v187
	v_add_f32_e32 v211, v129, v186
	v_lshlrev_b32_e32 v186, 16, v188
	v_add_f32_e32 v212, v122, v186
	v_and_b32_e32 v186, 0xffff0000, v188
	v_add_f32_e32 v213, v123, v186
	v_lshlrev_b32_e32 v186, 16, v189
	v_add_f32_e32 v214, v124, v186
	v_and_b32_e32 v186, 0xffff0000, v189
	v_add_f32_e32 v173, v126, v173
	v_add_f32_e32 v215, v125, v186
	v_cvt_pk_bf16_f32 v186, v173, v203
	v_cvt_pk_bf16_f32 v187, v210, v211
	v_cvt_pk_bf16_f32 v188, v212, v213
	v_cvt_pk_bf16_f32 v189, v214, v215
	global_store_dwordx4 v[208:209], v[186:189], off
	s_nop 1
	v_mul_f32_e32 v186, v203, v203
	v_fmac_f32_e32 v186, v173, v173
	v_mul_f32_e32 v173, v211, v211
	v_fmac_f32_e32 v173, v210, v210
	v_add_f32_e32 v173, v186, v173
	v_mul_f32_e32 v186, v213, v213
	v_fmac_f32_e32 v186, v212, v212
	v_add_f32_e32 v173, v186, v173
	v_mul_f32_e32 v186, v215, v215
	v_fmac_f32_e32 v186, v214, v214
	v_add_f32_e32 v173, v186, v173
	v_lshlrev_b32_e32 v186, 16, v204
	v_add_f32_e32 v203, v118, v186
	v_and_b32_e32 v186, 0xffff0000, v204
	v_add_f32_e32 v204, v119, v186
	v_lshlrev_b32_e32 v186, 16, v205
	v_add_f32_e32 v210, v120, v186
	v_and_b32_e32 v186, 0xffff0000, v205
	v_add_f32_e32 v205, v121, v186
	v_lshlrev_b32_e32 v186, 16, v206
	v_add_f32_e32 v211, v114, v186
	v_and_b32_e32 v186, 0xffff0000, v206
	v_add_f32_e32 v206, v115, v186
	v_lshlrev_b32_e32 v186, 16, v207
	v_add_f32_e32 v212, v116, v186
	v_and_b32_e32 v186, 0xffff0000, v207
	v_add_f32_e32 v207, v117, v186
	v_cvt_pk_bf16_f32 v186, v203, v204
	v_cvt_pk_bf16_f32 v187, v210, v205
	v_cvt_pk_bf16_f32 v188, v211, v206
	v_cvt_pk_bf16_f32 v189, v212, v207
	global_store_dwordx4 v[208:209], v[186:189], off offset:256
	s_nop 1
	v_mul_f32_e32 v186, v204, v204
	v_mul_f32_e32 v187, v205, v205
	v_fmac_f32_e32 v186, v203, v203
	v_fmac_f32_e32 v187, v210, v210
	v_add_f32_e32 v186, v186, v187
	v_mul_f32_e32 v187, v206, v206
	v_fmac_f32_e32 v187, v211, v211
	v_add_f32_e32 v186, v187, v186
	v_mul_f32_e32 v187, v207, v207
	v_fmac_f32_e32 v187, v212, v212
	v_add_f32_e32 v186, v187, v186
	v_add_f32_e32 v186, v173, v186
	v_xor_b32_e32 v173, 16, v190
	v_add_u32_e32 v187, 64, v191
	v_cmp_lt_i32_e32 vcc, v173, v187
	s_nop 1
	v_cndmask_b32_e32 v173, v190, v173, vcc
	v_lshlrev_b32_e32 v173, 2, v173
	ds_bpermute_b32 v188, v173, v186
	s_waitcnt lgkmcnt(0)
	v_add_f32_e32 v186, v186, v188
	v_xor_b32_e32 v188, 32, v190
	v_cmp_lt_i32_e32 vcc, v188, v187
	s_nop 1
	v_cndmask_b32_e32 v187, v190, v188, vcc
	v_lshlrev_b32_e32 v203, 2, v187
	ds_bpermute_b32 v187, v203, v186
	s_and_saveexec_b64 s[4:5], s[38:39]
	s_cbranch_execz .LBB0_236
	s_waitcnt lgkmcnt(0)
	v_add_f32_e32 v188, v186, v187
	s_lshl_b32 s6, s27, 2
	v_lshlrev_b64 v[186:187], 6, v[176:177]
	s_ashr_i32 s7, s6, 31
	v_lshl_add_u64 v[186:187], s[34:35], 0, v[186:187]
	v_lshl_add_u64 v[186:187], s[6:7], 2, v[186:187]
	s_lshl_b32 s94, s89, 2
	v_lshl_add_u64 v[186:187], v[186:187], 0, s[94:95]
	global_store_dword v[186:187], v188, off

; #define PG8_GAS __attribute__((address_space(1)))
; __device__ __forceinline__ unsigned cvt_pk_bf16(float lo, float hi) { unsigned r; asm volatile("v_cvt_pk_bf16_f32 %0, %1, %2" : "=v"(r) : "v"(lo), "v"(hi)); return r; }
;     __device__ __forceinline__ void operator()(const f32x4 (&acc)[2][2][4][2], const Unit& u, int wr, int wc, int fr, int fq) const {
;     ...
;             for (int m = 0; m < 4; ++m) {
;                 const int row = row0 + ai * HALF + m * 16; const size_t off = (size_t)row * 1024 + col0; float s = 0.f;
; #pragma unroll
;                 for (int bj = 0; bj < 2; ++bj) {
;                     f32x4 v0 = acc[ai][bj][m][0], v1 = acc[ai][bj][m][1]; const u32x4 b = bw[m][bj];
;                     v0[0] += __builtin_bit_cast(float, b.x << 16); v0[1] += __builtin_bit_cast(float, b.x & 0xffff0000u); v0[2] += __builtin_bit_cast(float, b.y << 16); v0[3] += __builtin_bit_cast(float, b.y & 0xffff0000u);
;                     v1[0] += __builtin_bit_cast(float, b.z << 16); v1[1] += __builtin_bit_cast(float, b.z & 0xffff0000u); v1[2] += __builtin_bit_cast(float, b.w << 16); v1[3] += __builtin_bit_cast(float, b.w & 0xffff0000u);
;                     u32x4 w; w.x = cvt_pk_bf16(v0[0], v0[1]); w.y = cvt_pk_bf16(v0[2], v0[3]); w.z = cvt_pk_bf16(v1[0], v1[1]); w.w = cvt_pk_bf16(v1[2], v1[3]);
;                     *(PG8_GAS u32x4*)(xb + off + bj * HALF) = w;
;                     s += (v0[0] * v0[0] + v0[1] * v0[1]) + (v0[2] * v0[2] + v0[3] * v0[3]) + (v1[0] * v1[0] + v1[1] * v1[1]) + (v1[2] * v1[2] + v1[3] * v1[3]); }
;                 s += __shfl_xor(s, 16); s += __shfl_xor(s, 32);
;                 if (fq == 0) ((PG8_GAS float*)ssq)[(size_t)row * 16 + u.pn * 4 + wc] = s; } }
.LBB0_242:
	s_or_b64 exec, exec, s[4:5]
	v_add_u32_e32 v186, 0x80, v176
	v_ashrrev_i32_e32 v187, 31, v186
	s_waitcnt lgkmcnt(0)
	v_lshlrev_b64 v[130:131], 11, v[186:187]
	v_lshl_add_u64 v[188:189], v[174:175], 0, v[130:131]
	v_add_u32_e32 v182, 0x90, v176
	v_ashrrev_i32_e32 v183, 31, v182
	v_add_u32_e32 v178, 0xa0, v176
	v_lshlrev_b64 v[130:131], 11, v[182:183]
	v_ashrrev_i32_e32 v179, 31, v178
	v_add_u32_e32 v176, 0xb0, v176
	v_lshl_add_u64 v[184:185], v[174:175], 0, v[130:131]
	v_lshlrev_b64 v[130:131], 11, v[178:179]
	v_ashrrev_i32_e32 v177, 31, v176
	v_lshl_add_u64 v[180:181], v[174:175], 0, v[130:131]
	v_lshlrev_b64 v[130:131], 11, v[176:177]
	v_lshl_add_u64 v[174:175], v[174:175], 0, v[130:131]
	s_waitcnt vmcnt(15)
	v_lshlrev_b32_e32 v208, 16, v216
	v_and_b32_e32 v216, 0xffff0000, v216
	v_add_f32_e32 v209, v63, v216
	v_lshlrev_b32_e32 v216, 16, v217
	v_add_f32_e32 v210, v64, v216
	v_and_b32_e32 v216, 0xffff0000, v217
	v_add_f32_e32 v211, v65, v216
	v_lshlrev_b32_e32 v216, 16, v218
	v_add_f32_e32 v212, v58, v216
	v_and_b32_e32 v216, 0xffff0000, v218
	v_add_f32_e32 v213, v59, v216
	v_lshlrev_b32_e32 v216, 16, v219
	v_add_f32_e32 v214, v60, v216
	v_and_b32_e32 v216, 0xffff0000, v219
	v_add_f32_e32 v208, v62, v208
	v_add_f32_e32 v215, v61, v216
	v_cvt_pk_bf16_f32 v216, v208, v209
	v_cvt_pk_bf16_f32 v217, v210, v211
	v_cvt_pk_bf16_f32 v218, v212, v213
	v_cvt_pk_bf16_f32 v219, v214, v215
	global_store_dwordx4 v[188:189], v[216:219], off
	s_nop 1
	v_mul_f32_e32 v216, v209, v209
	v_mul_f32_e32 v217, v211, v211
	v_fmac_f32_e32 v216, v208, v208
	v_fmac_f32_e32 v217, v210, v210
	v_add_f32_e32 v216, v216, v217
	v_mul_f32_e32 v217, v213, v213
	v_fmac_f32_e32 v217, v212, v212
	v_add_f32_e32 v216, v217, v216
	v_mul_f32_e32 v217, v215, v215
	v_fmac_f32_e32 v217, v214, v214
	v_add_f32_e32 v216, v217, v216
	s_waitcnt vmcnt(15)
	v_lshlrev_b32_e32 v217, 16, v220
	v_and_b32_e32 v220, 0xffff0000, v220
	v_add_f32_e32 v218, v55, v220
	v_lshlrev_b32_e32 v220, 16, v221
	v_add_f32_e32 v219, v56, v220
	v_and_b32_e32 v220, 0xffff0000, v221
	v_add_f32_e32 v208, v57, v220
	v_lshlrev_b32_e32 v220, 16, v222
	v_add_f32_e32 v209, v50, v220
	v_and_b32_e32 v220, 0xffff0000, v222
	v_add_f32_e32 v210, v51, v220
	v_lshlrev_b32_e32 v220, 16, v223
	v_add_f32_e32 v211, v52, v220
	v_and_b32_e32 v220, 0xffff0000, v223
	v_add_f32_e32 v217, v54, v217
	v_add_f32_e32 v212, v53, v220
	v_cvt_pk_bf16_f32 v220, v217, v218
	v_cvt_pk_bf16_f32 v221, v219, v208
	v_cvt_pk_bf16_f32 v222, v209, v210
	v_cvt_pk_bf16_f32 v223, v211, v212
	global_store_dwordx4 v[188:189], v[220:223], off offset:256
	s_nop 1
	v_mul_f32_e32 v220, v218, v218
	v_mul_f32_e32 v221, v208, v208
	v_fmac_f32_e32 v220, v217, v217
	v_fmac_f32_e32 v221, v219, v219
	v_add_f32_e32 v220, v220, v221
	v_mul_f32_e32 v221, v210, v210
	v_fmac_f32_e32 v221, v209, v209
	v_add_f32_e32 v220, v221, v220
	v_mul_f32_e32 v221, v212, v212
	v_fmac_f32_e32 v221, v211, v211
	v_add_f32_e32 v220, v221, v220
	v_add_f32_e32 v220, v216, v220
	ds_bpermute_b32 v221, v173, v220
	s_waitcnt lgkmcnt(0)
	v_add_f32_e32 v220, v220, v221
	ds_bpermute_b32 v221, v203, v220
	s_and_saveexec_b64 s[4:5], s[38:39]
	s_cbranch_execz .LBB0_244
	s_waitcnt lgkmcnt(0)
	v_add_f32_e32 v222, v220, v221
	s_lshl_b32 s6, s27, 2
	v_lshlrev_b64 v[220:221], 6, v[186:187]
	s_ashr_i32 s7, s6, 31
	v_lshl_add_u64 v[220:221], s[34:35], 0, v[220:221]
	v_lshl_add_u64 v[220:221], s[6:7], 2, v[220:221]
	s_lshl_b32 s94, s89, 2
	v_lshl_add_u64 v[220:221], v[220:221], 0, s[94:95]
	global_store_dword v[220:221], v222, off
.LBB0_244:
	s_or_b64 exec, exec, s[4:5]
	s_waitcnt vmcnt(15)
	v_lshlrev_b32_e32 v220, 16, v224
	v_and_b32_e32 v224, 0xffff0000, v224
	s_waitcnt lgkmcnt(0)
	v_add_f32_e32 v221, v47, v224
	v_lshlrev_b32_e32 v224, 16, v225
	v_add_f32_e32 v222, v48, v224
	v_and_b32_e32 v224, 0xffff0000, v225
	v_add_f32_e32 v223, v49, v224
	v_lshlrev_b32_e32 v224, 16, v226
	v_add_f32_e32 v186, v42, v224
	v_and_b32_e32 v224, 0xffff0000, v226
	v_add_f32_e32 v187, v43, v224
	v_lshlrev_b32_e32 v224, 16, v227
	v_add_f32_e32 v188, v44, v224
	v_and_b32_e32 v224, 0xffff0000, v227
	v_add_f32_e32 v220, v46, v220
	v_add_f32_e32 v189, v45, v224
	v_cvt_pk_bf16_f32 v224, v220, v221
	v_cvt_pk_bf16_f32 v225, v222, v223
	v_cvt_pk_bf16_f32 v226, v186, v187
	v_cvt_pk_bf16_f32 v227, v188, v189
	global_store_dwordx4 v[184:185], v[224:227], off
	s_nop 1
	v_mul_f32_e32 v224, v221, v221
	v_mul_f32_e32 v225, v223, v223
	v_fmac_f32_e32 v224, v220, v220
	v_fmac_f32_e32 v225, v222, v222
	v_add_f32_e32 v224, v224, v225
	v_mul_f32_e32 v225, v187, v187
	v_fmac_f32_e32 v225, v186, v186
	v_add_f32_e32 v224, v225, v224
	v_mul_f32_e32 v225, v189, v189
	v_fmac_f32_e32 v225, v188, v188
	v_add_f32_e32 v224, v225, v224
	s_waitcnt vmcnt(15)
	v_lshlrev_b32_e32 v225, 16, v228
	v_and_b32_e32 v228, 0xffff0000, v228
	v_add_f32_e32 v226, v39, v228
	v_lshlrev_b32_e32 v228, 16, v229
	v_add_f32_e32 v227, v40, v228
	v_and_b32_e32 v228, 0xffff0000, v229
	v_add_f32_e32 v220, v41, v228
	v_lshlrev_b32_e32 v228, 16, v230
	v_add_f32_e32 v221, v34, v228
	v_and_b32_e32 v228, 0xffff0000, v230
	v_add_f32_e32 v222, v35, v228
	v_lshlrev_b32_e32 v228, 16, v231
	v_add_f32_e32 v223, v36, v228
	v_and_b32_e32 v228, 0xffff0000, v231
	v_add_f32_e32 v225, v38, v225
	v_add_f32_e32 v186, v37, v228
	v_cvt_pk_bf16_f32 v228, v225, v226
	v_cvt_pk_bf16_f32 v229, v227, v220
	v_cvt_pk_bf16_f32 v230, v221, v222
	v_cvt_pk_bf16_f32 v231, v223, v186
	global_store_dwordx4 v[184:185], v[228:231], off offset:256
	s_nop 1
	v_mul_f32_e32 v228, v226, v226
	v_mul_f32_e32 v229, v220, v220
	v_fmac_f32_e32 v228, v225, v225
	v_fmac_f32_e32 v229, v227, v227
	v_add_f32_e32 v228, v228, v229
	v_mul_f32_e32 v229, v222, v222
	v_fmac_f32_e32 v229, v221, v221
	v_add_f32_e32 v228, v229, v228
	v_mul_f32_e32 v229, v186, v186
	v_fmac_f32_e32 v229, v223, v223
	v_add_f32_e32 v228, v229, v228
	v_add_f32_e32 v228, v224, v228
	ds_bpermute_b32 v229, v173, v228
	s_waitcnt lgkmcnt(0)
	v_add_f32_e32 v228, v228, v229
	ds_bpermute_b32 v229, v203, v228
	s_and_saveexec_b64 s[4:5], s[38:39]
	s_cbranch_execz .LBB0_246
	s_waitcnt lgkmcnt(0)
	v_add_f32_e32 v230, v228, v229
	s_lshl_b32 s6, s27, 2
	v_lshlrev_b64 v[228:229], 6, v[182:183]
	s_ashr_i32 s7, s6, 31
	v_lshl_add_u64 v[228:229], s[34:35], 0, v[228:229]
	v_lshl_add_u64 v[228:229], s[6:7], 2, v[228:229]
	s_lshl_b32 s94, s89, 2
	v_lshl_add_u64 v[228:229], v[228:229], 0, s[94:95]
	global_store_dword v[228:229], v230, off
; #define PG8_GAS __attribute__((address_space(1)))
; __device__ __forceinline__ unsigned cvt_pk_bf16(float lo, float hi) { unsigned r; asm volatile("v_cvt_pk_bf16_f32 %0, %1, %2" : "=v"(r) : "v"(lo), "v"(hi)); return r; }
;     __device__ __forceinline__ void operator()(const f32x4 (&acc)[2][2][4][2], const Unit& u, int wr, int wc, int fr, int fq) const {
;     ...
;             for (int m = 0; m < 4; ++m) {
;                 const int row = row0 + ai * HALF + m * 16; const size_t off = (size_t)row * 1024 + col0; float s = 0.f;
; #pragma unroll
;                 for (int bj = 0; bj < 2; ++bj) {
;                     f32x4 v0 = acc[ai][bj][m][0], v1 = acc[ai][bj][m][1]; const u32x4 b = bw[m][bj];
;                     v0[0] += __builtin_bit_cast(float, b.x << 16); v0[1] += __builtin_bit_cast(float, b.x & 0xffff0000u); v0[2] += __builtin_bit_cast(float, b.y << 16); v0[3] += __builtin_bit_cast(float, b.y & 0xffff0000u);
;                     v1[0] += __builtin_bit_cast(float, b.z << 16); v1[1] += __builtin_bit_cast(float, b.z & 0xffff0000u); v1[2] += __builtin_bit_cast(float, b.w << 16); v1[3] += __builtin_bit_cast(float, b.w & 0xffff0000u);
;                     u32x4 w; w.x = cvt_pk_bf16(v0[0], v0[1]); w.y = cvt_pk_bf16(v0[2], v0[3]); w.z = cvt_pk_bf16(v1[0], v1[1]); w.w = cvt_pk_bf16(v1[2], v1[3]);
;                     *(PG8_GAS u32x4*)(xb + off + bj * HALF) = w;
;                     s += (v0[0] * v0[0] + v0[1] * v0[1]) + (v0[2] * v0[2] + v0[3] * v0[3]) + (v1[0] * v1[0] + v1[1] * v1[1]) + (v1[2] * v1[2] + v1[3] * v1[3]); }
;                 s += __shfl_xor(s, 16); s += __shfl_xor(s, 32);
;                 if (fq == 0) ((PG8_GAS float*)ssq)[(size_t)row * 16 + u.pn * 4 + wc] = s; } }
.LBB0_246:
	s_or_b64 exec, exec, s[4:5]
	s_waitcnt vmcnt(15)
	v_lshlrev_b32_e32 v228, 16, v232
	v_and_b32_e32 v232, 0xffff0000, v232
	s_waitcnt lgkmcnt(0)
	v_add_f32_e32 v229, v31, v232
	v_lshlrev_b32_e32 v232, 16, v233
	v_add_f32_e32 v230, v32, v232
	v_and_b32_e32 v232, 0xffff0000, v233
	v_add_f32_e32 v231, v33, v232
	v_lshlrev_b32_e32 v232, 16, v234
	v_add_f32_e32 v224, v26, v232
	v_and_b32_e32 v232, 0xffff0000, v234
	v_add_f32_e32 v225, v27, v232
	v_lshlrev_b32_e32 v232, 16, v235
	v_add_f32_e32 v226, v28, v232
	v_and_b32_e32 v232, 0xffff0000, v235
	v_add_f32_e32 v228, v30, v228
	v_add_f32_e32 v227, v29, v232
	v_cvt_pk_bf16_f32 v232, v228, v229
	v_cvt_pk_bf16_f32 v233, v230, v231
	v_cvt_pk_bf16_f32 v234, v224, v225
	v_cvt_pk_bf16_f32 v235, v226, v227
	global_store_dwordx4 v[180:181], v[232:235], off
	s_nop 1
	v_mul_f32_e32 v232, v229, v229
	v_mul_f32_e32 v233, v231, v231
	v_fmac_f32_e32 v232, v228, v228
	v_fmac_f32_e32 v233, v230, v230
	v_add_f32_e32 v232, v232, v233
	v_mul_f32_e32 v233, v225, v225
	v_fmac_f32_e32 v233, v224, v224
	v_add_f32_e32 v232, v233, v232
	v_mul_f32_e32 v233, v227, v227
	v_fmac_f32_e32 v233, v226, v226
	v_add_f32_e32 v232, v233, v232
	s_waitcnt vmcnt(15)
	v_lshlrev_b32_e32 v233, 16, v236
	v_and_b32_e32 v236, 0xffff0000, v236
	v_add_f32_e32 v234, v23, v236
	v_lshlrev_b32_e32 v236, 16, v237
	v_add_f32_e32 v235, v24, v236
	v_and_b32_e32 v236, 0xffff0000, v237
	v_add_f32_e32 v228, v25, v236
	v_lshlrev_b32_e32 v236, 16, v238
	v_add_f32_e32 v229, v18, v236
	v_and_b32_e32 v236, 0xffff0000, v238
	v_add_f32_e32 v230, v19, v236
	v_lshlrev_b32_e32 v236, 16, v239
	v_add_f32_e32 v231, v20, v236
	v_and_b32_e32 v236, 0xffff0000, v239
	v_add_f32_e32 v233, v22, v233
	v_add_f32_e32 v224, v21, v236
	v_cvt_pk_bf16_f32 v236, v233, v234
	v_cvt_pk_bf16_f32 v237, v235, v228
	v_cvt_pk_bf16_f32 v238, v229, v230
	v_cvt_pk_bf16_f32 v239, v231, v224
	global_store_dwordx4 v[180:181], v[236:239], off offset:256
	s_nop 1
	v_mul_f32_e32 v236, v234, v234
	v_mul_f32_e32 v237, v228, v228
	v_fmac_f32_e32 v236, v233, v233
	v_fmac_f32_e32 v237, v235, v235
	v_add_f32_e32 v236, v236, v237
	v_mul_f32_e32 v237, v230, v230
	v_fmac_f32_e32 v237, v229, v229
	v_add_f32_e32 v236, v237, v236
	v_mul_f32_e32 v237, v224, v224
	v_fmac_f32_e32 v237, v231, v231
	v_add_f32_e32 v236, v237, v236
	v_add_f32_e32 v236, v232, v236
	ds_bpermute_b32 v237, v173, v236
	s_waitcnt lgkmcnt(0)
	v_add_f32_e32 v236, v236, v237
	ds_bpermute_b32 v237, v203, v236
	s_and_saveexec_b64 s[4:5], s[38:39]
	s_cbranch_execz .LBB0_248
	s_waitcnt lgkmcnt(0)
	v_add_f32_e32 v238, v236, v237
	s_lshl_b32 s6, s27, 2
	v_lshlrev_b64 v[236:237], 6, v[178:179]
	s_ashr_i32 s7, s6, 31
	v_lshl_add_u64 v[236:237], s[34:35], 0, v[236:237]
	v_lshl_add_u64 v[236:237], s[6:7], 2, v[236:237]
	s_lshl_b32 s94, s89, 2
	v_lshl_add_u64 v[236:237], v[236:237], 0, s[94:95]
	global_store_dword v[236:237], v238, off
.LBB0_248:
	s_or_b64 exec, exec, s[4:5]
	s_waitcnt vmcnt(15)
	v_lshlrev_b32_e32 v236, 16, v240
	v_and_b32_e32 v240, 0xffff0000, v240
	s_waitcnt lgkmcnt(0)
	v_add_f32_e32 v237, v15, v240
	v_lshlrev_b32_e32 v240, 16, v241
	v_add_f32_e32 v238, v16, v240
	v_and_b32_e32 v240, 0xffff0000, v241
	v_add_f32_e32 v239, v17, v240
	v_lshlrev_b32_e32 v240, 16, v242
	v_add_f32_e32 v232, v10, v240
	v_and_b32_e32 v240, 0xffff0000, v242
	v_add_f32_e32 v233, v11, v240
	v_lshlrev_b32_e32 v240, 16, v243
	v_add_f32_e32 v234, v12, v240
	v_and_b32_e32 v240, 0xffff0000, v243
	v_add_f32_e32 v236, v14, v236
	v_add_f32_e32 v235, v13, v240
	v_cvt_pk_bf16_f32 v240, v236, v237
	v_cvt_pk_bf16_f32 v241, v238, v239
	v_cvt_pk_bf16_f32 v242, v232, v233
	v_cvt_pk_bf16_f32 v243, v234, v235
	global_store_dwordx4 v[174:175], v[240:243], off
	s_nop 1
	v_mul_f32_e32 v240, v237, v237
	v_mul_f32_e32 v241, v239, v239
	v_fmac_f32_e32 v240, v236, v236
	v_fmac_f32_e32 v241, v238, v238
	v_add_f32_e32 v240, v240, v241
	v_mul_f32_e32 v241, v233, v233
	v_fmac_f32_e32 v241, v232, v232
	v_add_f32_e32 v240, v241, v240
	v_mul_f32_e32 v241, v235, v235
	v_fmac_f32_e32 v241, v234, v234
	v_add_f32_e32 v240, v241, v240
	s_waitcnt vmcnt(15)
	v_lshlrev_b32_e32 v241, 16, v244
	v_and_b32_e32 v244, 0xffff0000, v244
	v_add_f32_e32 v242, v7, v244
	v_lshlrev_b32_e32 v244, 16, v245
	v_add_f32_e32 v243, v8, v244
	v_and_b32_e32 v244, 0xffff0000, v245
	v_add_f32_e32 v236, v9, v244
	v_lshlrev_b32_e32 v244, 16, v246
	v_add_f32_e32 v237, v2, v244
	v_and_b32_e32 v244, 0xffff0000, v246
	v_add_f32_e32 v238, v3, v244
	v_lshlrev_b32_e32 v244, 16, v247
	v_add_f32_e32 v239, v4, v244
	v_and_b32_e32 v244, 0xffff0000, v247
	v_add_f32_e32 v241, v6, v241
	v_add_f32_e32 v232, v5, v244
	v_cvt_pk_bf16_f32 v244, v241, v242
	v_cvt_pk_bf16_f32 v245, v243, v236
	v_cvt_pk_bf16_f32 v246, v237, v238
	v_cvt_pk_bf16_f32 v247, v239, v232
	global_store_dwordx4 v[174:175], v[244:247], off offset:256
	s_nop 1
	v_mul_f32_e32 v244, v242, v242
	v_mul_f32_e32 v245, v236, v236
	v_fmac_f32_e32 v244, v241, v241
	v_fmac_f32_e32 v245, v243, v243
	v_add_f32_e32 v244, v244, v245
	v_mul_f32_e32 v245, v238, v238
	v_fmac_f32_e32 v245, v237, v237
	v_add_f32_e32 v244, v245, v244
	v_mul_f32_e32 v245, v232, v232
	v_fmac_f32_e32 v245, v239, v239
	v_add_f32_e32 v244, v245, v244
	v_add_f32_e32 v244, v240, v244
	ds_bpermute_b32 v245, v173, v244
	s_waitcnt lgkmcnt(0)
	v_add_f32_e32 v244, v244, v245
	ds_bpermute_b32 v245, v203, v244
	s_and_saveexec_b64 s[4:5], s[38:39]
	s_cbranch_execz .LBB0_250
	s_waitcnt lgkmcnt(0)
	v_add_f32_e32 v246, v244, v245
	s_lshl_b32 s6, s27, 2
	v_lshlrev_b64 v[244:245], 6, v[176:177]
	s_ashr_i32 s7, s6, 31
	v_lshl_add_u64 v[244:245], s[34:35], 0, v[244:245]
	v_lshl_add_u64 v[244:245], s[6:7], 2, v[244:245]
	s_lshl_b32 s94, s89, 2
	v_lshl_add_u64 v[244:245], v[244:245], 0, s[94:95]
	global_store_dword v[244:245], v246, off
